# residual epilogue (P4/P7): v_permlane16_swap pairs turn 32 dwordx2 stores into 16 dwordx4 stores per tile
# speedup vs baseline: 1.0134x; 1.0088x over previous
; __device__ __forceinline__ unsigned pk2(float lo, float hi) { const bf16x2_t v = __builtin_convertvector((f32x2_t){lo, hi}, bf16x2_t); return __builtin_bit_cast(unsigned, v); }
; __device__ __forceinline__ float bf_lo(unsigned w) { return __uint_as_float(w << 16); }
; __device__ __forceinline__ float bf_hi(unsigned w) { return __uint_as_float(w & 0xffff0000u); }
;     __device__ __forceinline__ void row(int ai, int m, const f32x4 (&v)[2][2], const Unit& u, int wr, int wc, int fr, int fq) const {
;         const int row0 = u.pm * BM + wr * 64 + fr, col0 = u.pn * BM + wc * 32 + 4 * fq;
;         const size_t off = (size_t)(row0 + ai * HALF + m * 16) * DM + col0;
; #pragma unroll
;         for (int bj = 0; bj < 2; ++bj)
; #pragma unroll
;             for (int n = 0; n < 2; ++n) { const u32x2 rb = *(const u32x2*)(res + off + bj * HALF + n * 16);
;                 const f32x4 r = (f32x4){bf_lo(rb.x), bf_hi(rb.x), bf_lo(rb.y), bf_hi(rb.y)}; const f32x4 o = v[bj][n] + ALPHA * r;
;                 u32x2 w; w.x = pk2(o[0], o[1]); w.y = pk2(o[2], o[3]); *(u32x2*)(C + off + bj * HALF + n * 16) = w; }
;     }
.LBB0_912:
	v_lshl_add_u32 v142, s30, 8, v144
	v_lshl_add_u32 v140, s28, 8, v146
	v_lshl_add_u32 v140, v142, 12, v140
	v_lshlrev_b32_e32 v140, 1, v140
	v_add_u32_e32 v141, 0x20000, v140
	v_add_u32_e32 v142, 0x40000, v140
	v_add_u32_e32 v143, 0x60000, v140
	v_add_u32_e32 v150, 0x100000, v140
	v_add_u32_e32 v151, 0x120000, v140
	v_add_u32_e32 v152, 0x140000, v140
	v_add_u32_e32 v153, 0x160000, v140
	v_mbcnt_lo_u32_b32 v222, -1, 0
	v_mbcnt_hi_u32_b32 v222, -1, v222
	v_bfe_u32 v222, v222, 4, 1
	v_mul_u32_u24_e32 v222, 24, v222
	v_add_u32_e32 v223, v140, v222
	v_add_u32_e32 v224, v141, v222
	v_add_u32_e32 v225, v142, v222
	v_add_u32_e32 v226, v143, v222
	v_add_u32_e32 v227, v150, v222
	v_add_u32_e32 v228, v151, v222
	v_add_u32_e32 v229, v152, v222
	v_add_u32_e32 v230, v153, v222
	global_load_dwordx2 v[154:155], v140, s[50:51]
	global_load_dwordx2 v[156:157], v140, s[50:51] offset:32
	global_load_dwordx2 v[158:159], v140, s[50:51] offset:256
	global_load_dwordx2 v[160:161], v140, s[50:51] offset:288
	global_load_dwordx2 v[162:163], v141, s[50:51]
	global_load_dwordx2 v[164:165], v141, s[50:51] offset:32
	global_load_dwordx2 v[166:167], v141, s[50:51] offset:256
	global_load_dwordx2 v[168:169], v141, s[50:51] offset:288
	global_load_dwordx2 v[170:171], v142, s[50:51]
	global_load_dwordx2 v[172:173], v142, s[50:51] offset:32
	global_load_dwordx2 v[174:175], v142, s[50:51] offset:256
	global_load_dwordx2 v[176:177], v142, s[50:51] offset:288
	global_load_dwordx2 v[178:179], v143, s[50:51]
	global_load_dwordx2 v[180:181], v143, s[50:51] offset:32
	global_load_dwordx2 v[182:183], v143, s[50:51] offset:256
	global_load_dwordx2 v[184:185], v143, s[50:51] offset:288
	global_load_dwordx2 v[186:187], v150, s[50:51]
	global_load_dwordx2 v[188:189], v150, s[50:51] offset:32
	global_load_dwordx2 v[194:195], v150, s[50:51] offset:256
	global_load_dwordx2 v[196:197], v150, s[50:51] offset:288
	global_load_dwordx2 v[198:199], v151, s[50:51]
	global_load_dwordx2 v[200:201], v151, s[50:51] offset:32
	global_load_dwordx2 v[202:203], v151, s[50:51] offset:256
	global_load_dwordx2 v[204:205], v151, s[50:51] offset:288
	global_load_dwordx2 v[206:207], v152, s[50:51]
	global_load_dwordx2 v[208:209], v152, s[50:51] offset:32
	global_load_dwordx2 v[210:211], v152, s[50:51] offset:256
	global_load_dwordx2 v[212:213], v152, s[50:51] offset:288
	global_load_dwordx2 v[214:215], v153, s[50:51]
	global_load_dwordx2 v[216:217], v153, s[50:51] offset:32
	global_load_dwordx2 v[218:219], v153, s[50:51] offset:256
	global_load_dwordx2 v[220:221], v153, s[50:51] offset:288
	s_waitcnt vmcnt(30)
	v_lshlrev_b32_e32 v190, 16, v154
	v_and_b32_e32 v191, 0xffff0000, v154
	v_lshlrev_b32_e32 v154, 16, v155
	v_and_b32_e32 v155, 0xffff0000, v155
	v_pk_fma_f32 v[154:155], v[154:155], s[16:17], v[126:127] op_sel_hi:[1,0,1]
	v_pk_fma_f32 v[190:191], v[190:191], s[16:17], v[124:125] op_sel_hi:[1,0,1]
	s_nop 0
	v_cvt_pk_bf16_f32 v155, v154, v155
	v_cvt_pk_bf16_f32 v154, v190, v191
	v_lshlrev_b32_e32 v190, 16, v156
	v_and_b32_e32 v191, 0xffff0000, v156
	v_lshlrev_b32_e32 v156, 16, v157
	v_and_b32_e32 v157, 0xffff0000, v157
	v_pk_fma_f32 v[156:157], v[156:157], s[16:17], v[122:123] op_sel_hi:[1,0,1]
	v_pk_fma_f32 v[190:191], v[190:191], s[16:17], v[120:121] op_sel_hi:[1,0,1]
	s_nop 0
	v_cvt_pk_bf16_f32 v157, v156, v157
	v_cvt_pk_bf16_f32 v156, v190, v191
	s_nop 1
	v_permlane16_swap_b32_e32 v154, v156
	v_permlane16_swap_b32_e32 v155, v157
	global_store_dwordx4 v223, v[154:157], s[52:53]
	s_waitcnt vmcnt(29)
	v_lshlrev_b32_e32 v190, 16, v158
	v_and_b32_e32 v191, 0xffff0000, v158
	v_lshlrev_b32_e32 v158, 16, v159
	v_and_b32_e32 v159, 0xffff0000, v159
	v_pk_fma_f32 v[158:159], v[158:159], s[16:17], v[94:95] op_sel_hi:[1,0,1]
	v_pk_fma_f32 v[190:191], v[190:191], s[16:17], v[92:93] op_sel_hi:[1,0,1]
	s_nop 0
	v_cvt_pk_bf16_f32 v159, v158, v159
	v_cvt_pk_bf16_f32 v158, v190, v191
	v_lshlrev_b32_e32 v190, 16, v160
	v_and_b32_e32 v191, 0xffff0000, v160
	v_lshlrev_b32_e32 v160, 16, v161
	v_and_b32_e32 v161, 0xffff0000, v161
	v_pk_fma_f32 v[160:161], v[160:161], s[16:17], v[90:91] op_sel_hi:[1,0,1]
	v_pk_fma_f32 v[190:191], v[190:191], s[16:17], v[88:89] op_sel_hi:[1,0,1]
	s_nop 0
	v_cvt_pk_bf16_f32 v161, v160, v161
	v_cvt_pk_bf16_f32 v160, v190, v191
	s_nop 1
	v_permlane16_swap_b32_e32 v158, v160
	v_permlane16_swap_b32_e32 v159, v161
	global_store_dwordx4 v223, v[158:161], s[52:53] offset:256
	s_waitcnt vmcnt(28)
	v_lshlrev_b32_e32 v190, 16, v162
	v_and_b32_e32 v191, 0xffff0000, v162
	v_lshlrev_b32_e32 v162, 16, v163
	v_and_b32_e32 v163, 0xffff0000, v163
	v_pk_fma_f32 v[162:163], v[162:163], s[16:17], v[118:119] op_sel_hi:[1,0,1]
	v_pk_fma_f32 v[190:191], v[190:191], s[16:17], v[116:117] op_sel_hi:[1,0,1]
	s_nop 0
	v_cvt_pk_bf16_f32 v163, v162, v163
	v_cvt_pk_bf16_f32 v162, v190, v191
	v_lshlrev_b32_e32 v190, 16, v164
	v_and_b32_e32 v191, 0xffff0000, v164
	v_lshlrev_b32_e32 v164, 16, v165
	v_and_b32_e32 v165, 0xffff0000, v165
	v_pk_fma_f32 v[164:165], v[164:165], s[16:17], v[114:115] op_sel_hi:[1,0,1]
	v_pk_fma_f32 v[190:191], v[190:191], s[16:17], v[112:113] op_sel_hi:[1,0,1]
	s_nop 0
	v_cvt_pk_bf16_f32 v165, v164, v165
	v_cvt_pk_bf16_f32 v164, v190, v191
	s_nop 1
	v_permlane16_swap_b32_e32 v162, v164
	v_permlane16_swap_b32_e32 v163, v165
	global_store_dwordx4 v224, v[162:165], s[52:53]
	s_waitcnt vmcnt(27)
; __device__ __forceinline__ unsigned pk2(float lo, float hi) { const bf16x2_t v = __builtin_convertvector((f32x2_t){lo, hi}, bf16x2_t); return __builtin_bit_cast(unsigned, v); }
; __device__ __forceinline__ float bf_lo(unsigned w) { return __uint_as_float(w << 16); }
; __device__ __forceinline__ float bf_hi(unsigned w) { return __uint_as_float(w & 0xffff0000u); }
;     __device__ __forceinline__ void row(int ai, int m, const f32x4 (&v)[2][2], const Unit& u, int wr, int wc, int fr, int fq) const {
;         const int row0 = u.pm * BM + wr * 64 + fr, col0 = u.pn * BM + wc * 32 + 4 * fq;
;         const size_t off = (size_t)(row0 + ai * HALF + m * 16) * DM + col0;
; #pragma unroll
;         for (int bj = 0; bj < 2; ++bj)
; #pragma unroll
;             for (int n = 0; n < 2; ++n) { const u32x2 rb = *(const u32x2*)(res + off + bj * HALF + n * 16);
;                 const f32x4 r = (f32x4){bf_lo(rb.x), bf_hi(rb.x), bf_lo(rb.y), bf_hi(rb.y)}; const f32x4 o = v[bj][n] + ALPHA * r;
;                 u32x2 w; w.x = pk2(o[0], o[1]); w.y = pk2(o[2], o[3]); *(u32x2*)(C + off + bj * HALF + n * 16) = w; }
;     }
	v_lshlrev_b32_e32 v190, 16, v166
	v_and_b32_e32 v191, 0xffff0000, v166
	v_lshlrev_b32_e32 v166, 16, v167
	v_and_b32_e32 v167, 0xffff0000, v167
	v_pk_fma_f32 v[166:167], v[166:167], s[16:17], v[86:87] op_sel_hi:[1,0,1]
	v_pk_fma_f32 v[190:191], v[190:191], s[16:17], v[84:85] op_sel_hi:[1,0,1]
	s_nop 0
	v_cvt_pk_bf16_f32 v167, v166, v167
	v_cvt_pk_bf16_f32 v166, v190, v191
	v_lshlrev_b32_e32 v190, 16, v168
	v_and_b32_e32 v191, 0xffff0000, v168
	v_lshlrev_b32_e32 v168, 16, v169
	v_and_b32_e32 v169, 0xffff0000, v169
	v_pk_fma_f32 v[168:169], v[168:169], s[16:17], v[82:83] op_sel_hi:[1,0,1]
	v_pk_fma_f32 v[190:191], v[190:191], s[16:17], v[80:81] op_sel_hi:[1,0,1]
	s_nop 0
	v_cvt_pk_bf16_f32 v169, v168, v169
	v_cvt_pk_bf16_f32 v168, v190, v191
	s_nop 1
	v_permlane16_swap_b32_e32 v166, v168
	v_permlane16_swap_b32_e32 v167, v169
	global_store_dwordx4 v224, v[166:169], s[52:53] offset:256
	s_waitcnt vmcnt(26)
	v_lshlrev_b32_e32 v190, 16, v170
	v_and_b32_e32 v191, 0xffff0000, v170
	v_lshlrev_b32_e32 v170, 16, v171
	v_and_b32_e32 v171, 0xffff0000, v171
	v_pk_fma_f32 v[170:171], v[170:171], s[16:17], v[110:111] op_sel_hi:[1,0,1]
	v_pk_fma_f32 v[190:191], v[190:191], s[16:17], v[108:109] op_sel_hi:[1,0,1]
	s_nop 0
	v_cvt_pk_bf16_f32 v171, v170, v171
	v_cvt_pk_bf16_f32 v170, v190, v191
	v_lshlrev_b32_e32 v190, 16, v172
	v_and_b32_e32 v191, 0xffff0000, v172
	v_lshlrev_b32_e32 v172, 16, v173
	v_and_b32_e32 v173, 0xffff0000, v173
	v_pk_fma_f32 v[172:173], v[172:173], s[16:17], v[106:107] op_sel_hi:[1,0,1]
	v_pk_fma_f32 v[190:191], v[190:191], s[16:17], v[104:105] op_sel_hi:[1,0,1]
	s_nop 0
	v_cvt_pk_bf16_f32 v173, v172, v173
	v_cvt_pk_bf16_f32 v172, v190, v191
	s_nop 1
	v_permlane16_swap_b32_e32 v170, v172
	v_permlane16_swap_b32_e32 v171, v173
	global_store_dwordx4 v225, v[170:173], s[52:53]
	s_waitcnt vmcnt(25)
	v_lshlrev_b32_e32 v190, 16, v174
	v_and_b32_e32 v191, 0xffff0000, v174
	v_lshlrev_b32_e32 v174, 16, v175
	v_and_b32_e32 v175, 0xffff0000, v175
	v_pk_fma_f32 v[174:175], v[174:175], s[16:17], v[78:79] op_sel_hi:[1,0,1]
	v_pk_fma_f32 v[190:191], v[190:191], s[16:17], v[76:77] op_sel_hi:[1,0,1]
	s_nop 0
	v_cvt_pk_bf16_f32 v175, v174, v175
	v_cvt_pk_bf16_f32 v174, v190, v191
	v_lshlrev_b32_e32 v190, 16, v176
	v_and_b32_e32 v191, 0xffff0000, v176
	v_lshlrev_b32_e32 v176, 16, v177
	v_and_b32_e32 v177, 0xffff0000, v177
	v_pk_fma_f32 v[176:177], v[176:177], s[16:17], v[74:75] op_sel_hi:[1,0,1]
	v_pk_fma_f32 v[190:191], v[190:191], s[16:17], v[72:73] op_sel_hi:[1,0,1]
	s_nop 0
	v_cvt_pk_bf16_f32 v177, v176, v177
	v_cvt_pk_bf16_f32 v176, v190, v191
	s_nop 1
	v_permlane16_swap_b32_e32 v174, v176
	v_permlane16_swap_b32_e32 v175, v177
	global_store_dwordx4 v225, v[174:177], s[52:53] offset:256
	s_waitcnt vmcnt(24)
	v_lshlrev_b32_e32 v190, 16, v178
	v_and_b32_e32 v191, 0xffff0000, v178
	v_lshlrev_b32_e32 v178, 16, v179
	v_and_b32_e32 v179, 0xffff0000, v179
	v_pk_fma_f32 v[178:179], v[178:179], s[16:17], v[102:103] op_sel_hi:[1,0,1]
	v_pk_fma_f32 v[190:191], v[190:191], s[16:17], v[100:101] op_sel_hi:[1,0,1]
	s_nop 0
	v_cvt_pk_bf16_f32 v179, v178, v179
	v_cvt_pk_bf16_f32 v178, v190, v191
	v_lshlrev_b32_e32 v190, 16, v180
	v_and_b32_e32 v191, 0xffff0000, v180
	v_lshlrev_b32_e32 v180, 16, v181
	v_and_b32_e32 v181, 0xffff0000, v181
	v_pk_fma_f32 v[180:181], v[180:181], s[16:17], v[98:99] op_sel_hi:[1,0,1]
	v_pk_fma_f32 v[190:191], v[190:191], s[16:17], v[96:97] op_sel_hi:[1,0,1]
	s_nop 0
	v_cvt_pk_bf16_f32 v181, v180, v181
	v_cvt_pk_bf16_f32 v180, v190, v191
	s_nop 1
	v_permlane16_swap_b32_e32 v178, v180
	v_permlane16_swap_b32_e32 v179, v181
	global_store_dwordx4 v226, v[178:181], s[52:53]
	s_waitcnt vmcnt(23)
	v_lshlrev_b32_e32 v190, 16, v182
	v_and_b32_e32 v191, 0xffff0000, v182
	v_lshlrev_b32_e32 v182, 16, v183
	v_and_b32_e32 v183, 0xffff0000, v183
	v_pk_fma_f32 v[182:183], v[182:183], s[16:17], v[70:71] op_sel_hi:[1,0,1]
	v_pk_fma_f32 v[190:191], v[190:191], s[16:17], v[68:69] op_sel_hi:[1,0,1]
	s_nop 0
	v_cvt_pk_bf16_f32 v183, v182, v183
	v_cvt_pk_bf16_f32 v182, v190, v191
	v_lshlrev_b32_e32 v190, 16, v184
	v_and_b32_e32 v191, 0xffff0000, v184
	v_lshlrev_b32_e32 v184, 16, v185
	v_and_b32_e32 v185, 0xffff0000, v185
	v_pk_fma_f32 v[184:185], v[184:185], s[16:17], v[66:67] op_sel_hi:[1,0,1]
	v_pk_fma_f32 v[190:191], v[190:191], s[16:17], v[64:65] op_sel_hi:[1,0,1]
	s_nop 0
	v_cvt_pk_bf16_f32 v185, v184, v185
	v_cvt_pk_bf16_f32 v184, v190, v191
	s_nop 1
	v_permlane16_swap_b32_e32 v182, v184
	v_permlane16_swap_b32_e32 v183, v185
	global_store_dwordx4 v226, v[182:185], s[52:53] offset:256
	s_waitcnt vmcnt(22)
	v_lshlrev_b32_e32 v190, 16, v186
	v_and_b32_e32 v191, 0xffff0000, v186
	v_lshlrev_b32_e32 v186, 16, v187
	v_and_b32_e32 v187, 0xffff0000, v187
	v_pk_fma_f32 v[186:187], v[186:187], s[16:17], v[62:63] op_sel_hi:[1,0,1]
	v_pk_fma_f32 v[190:191], v[190:191], s[16:17], v[60:61] op_sel_hi:[1,0,1]
	s_nop 0
	v_cvt_pk_bf16_f32 v187, v186, v187
	v_cvt_pk_bf16_f32 v186, v190, v191
	v_lshlrev_b32_e32 v190, 16, v188
	v_and_b32_e32 v191, 0xffff0000, v188
	v_lshlrev_b32_e32 v188, 16, v189
	v_and_b32_e32 v189, 0xffff0000, v189
	v_pk_fma_f32 v[188:189], v[188:189], s[16:17], v[58:59] op_sel_hi:[1,0,1]
	v_pk_fma_f32 v[190:191], v[190:191], s[16:17], v[56:57] op_sel_hi:[1,0,1]
	s_nop 0
	v_cvt_pk_bf16_f32 v189, v188, v189
	v_cvt_pk_bf16_f32 v188, v190, v191
	s_nop 1
	v_permlane16_swap_b32_e32 v186, v188
	v_permlane16_swap_b32_e32 v187, v189
	global_store_dwordx4 v227, v[186:189], s[52:53]
	s_waitcnt vmcnt(21)
; __device__ __forceinline__ unsigned pk2(float lo, float hi) { const bf16x2_t v = __builtin_convertvector((f32x2_t){lo, hi}, bf16x2_t); return __builtin_bit_cast(unsigned, v); }
; __device__ __forceinline__ float bf_lo(unsigned w) { return __uint_as_float(w << 16); }
; __device__ __forceinline__ float bf_hi(unsigned w) { return __uint_as_float(w & 0xffff0000u); }
;     __device__ __forceinline__ void row(int ai, int m, const f32x4 (&v)[2][2], const Unit& u, int wr, int wc, int fr, int fq) const {
;         const int row0 = u.pm * BM + wr * 64 + fr, col0 = u.pn * BM + wc * 32 + 4 * fq;
;         const size_t off = (size_t)(row0 + ai * HALF + m * 16) * DM + col0;
; #pragma unroll
;         for (int bj = 0; bj < 2; ++bj)
; #pragma unroll
;             for (int n = 0; n < 2; ++n) { const u32x2 rb = *(const u32x2*)(res + off + bj * HALF + n * 16);
;                 const f32x4 r = (f32x4){bf_lo(rb.x), bf_hi(rb.x), bf_lo(rb.y), bf_hi(rb.y)}; const f32x4 o = v[bj][n] + ALPHA * r;
;                 u32x2 w; w.x = pk2(o[0], o[1]); w.y = pk2(o[2], o[3]); *(u32x2*)(C + off + bj * HALF + n * 16) = w; }
;     }
	v_lshlrev_b32_e32 v190, 16, v194
	v_and_b32_e32 v191, 0xffff0000, v194
	v_lshlrev_b32_e32 v194, 16, v195
	v_and_b32_e32 v195, 0xffff0000, v195
	v_pk_fma_f32 v[194:195], v[194:195], s[16:17], v[30:31] op_sel_hi:[1,0,1]
	v_pk_fma_f32 v[190:191], v[190:191], s[16:17], v[28:29] op_sel_hi:[1,0,1]
	s_nop 0
	v_cvt_pk_bf16_f32 v195, v194, v195
	v_cvt_pk_bf16_f32 v194, v190, v191
	v_lshlrev_b32_e32 v190, 16, v196
	v_and_b32_e32 v191, 0xffff0000, v196
	v_lshlrev_b32_e32 v196, 16, v197
	v_and_b32_e32 v197, 0xffff0000, v197
	v_pk_fma_f32 v[196:197], v[196:197], s[16:17], v[26:27] op_sel_hi:[1,0,1]
	v_pk_fma_f32 v[190:191], v[190:191], s[16:17], v[24:25] op_sel_hi:[1,0,1]
	s_nop 0
	v_cvt_pk_bf16_f32 v197, v196, v197
	v_cvt_pk_bf16_f32 v196, v190, v191
	s_nop 1
	v_permlane16_swap_b32_e32 v194, v196
	v_permlane16_swap_b32_e32 v195, v197
	global_store_dwordx4 v227, v[194:197], s[52:53] offset:256
	s_waitcnt vmcnt(20)
	v_lshlrev_b32_e32 v190, 16, v198
	v_and_b32_e32 v191, 0xffff0000, v198
	v_lshlrev_b32_e32 v198, 16, v199
	v_and_b32_e32 v199, 0xffff0000, v199
	v_pk_fma_f32 v[198:199], v[198:199], s[16:17], v[54:55] op_sel_hi:[1,0,1]
	v_pk_fma_f32 v[190:191], v[190:191], s[16:17], v[52:53] op_sel_hi:[1,0,1]
	s_nop 0
	v_cvt_pk_bf16_f32 v199, v198, v199
	v_cvt_pk_bf16_f32 v198, v190, v191
	v_lshlrev_b32_e32 v190, 16, v200
	v_and_b32_e32 v191, 0xffff0000, v200
	v_lshlrev_b32_e32 v200, 16, v201
	v_and_b32_e32 v201, 0xffff0000, v201
	v_pk_fma_f32 v[200:201], v[200:201], s[16:17], v[50:51] op_sel_hi:[1,0,1]
	v_pk_fma_f32 v[190:191], v[190:191], s[16:17], v[48:49] op_sel_hi:[1,0,1]
	s_nop 0
	v_cvt_pk_bf16_f32 v201, v200, v201
	v_cvt_pk_bf16_f32 v200, v190, v191
	s_nop 1
	v_permlane16_swap_b32_e32 v198, v200
	v_permlane16_swap_b32_e32 v199, v201
	global_store_dwordx4 v228, v[198:201], s[52:53]
	s_waitcnt vmcnt(19)
	v_lshlrev_b32_e32 v190, 16, v202
	v_and_b32_e32 v191, 0xffff0000, v202
	v_lshlrev_b32_e32 v202, 16, v203
	v_and_b32_e32 v203, 0xffff0000, v203
	v_pk_fma_f32 v[202:203], v[202:203], s[16:17], v[22:23] op_sel_hi:[1,0,1]
	v_pk_fma_f32 v[190:191], v[190:191], s[16:17], v[20:21] op_sel_hi:[1,0,1]
	s_nop 0
	v_cvt_pk_bf16_f32 v203, v202, v203
	v_cvt_pk_bf16_f32 v202, v190, v191
	v_lshlrev_b32_e32 v190, 16, v204
	v_and_b32_e32 v191, 0xffff0000, v204
	v_lshlrev_b32_e32 v204, 16, v205
	v_and_b32_e32 v205, 0xffff0000, v205
	v_pk_fma_f32 v[204:205], v[204:205], s[16:17], v[18:19] op_sel_hi:[1,0,1]
	v_pk_fma_f32 v[190:191], v[190:191], s[16:17], v[16:17] op_sel_hi:[1,0,1]
	s_nop 0
	v_cvt_pk_bf16_f32 v205, v204, v205
	v_cvt_pk_bf16_f32 v204, v190, v191
	s_nop 1
	v_permlane16_swap_b32_e32 v202, v204
	v_permlane16_swap_b32_e32 v203, v205
	global_store_dwordx4 v228, v[202:205], s[52:53] offset:256
	s_waitcnt vmcnt(18)
	v_lshlrev_b32_e32 v190, 16, v206
	v_and_b32_e32 v191, 0xffff0000, v206
	v_lshlrev_b32_e32 v206, 16, v207
	v_and_b32_e32 v207, 0xffff0000, v207
	v_pk_fma_f32 v[206:207], v[206:207], s[16:17], v[46:47] op_sel_hi:[1,0,1]
	v_pk_fma_f32 v[190:191], v[190:191], s[16:17], v[44:45] op_sel_hi:[1,0,1]
	s_nop 0
	v_cvt_pk_bf16_f32 v207, v206, v207
	v_cvt_pk_bf16_f32 v206, v190, v191
	v_lshlrev_b32_e32 v190, 16, v208
	v_and_b32_e32 v191, 0xffff0000, v208
	v_lshlrev_b32_e32 v208, 16, v209
	v_and_b32_e32 v209, 0xffff0000, v209
	v_pk_fma_f32 v[208:209], v[208:209], s[16:17], v[42:43] op_sel_hi:[1,0,1]
	v_pk_fma_f32 v[190:191], v[190:191], s[16:17], v[40:41] op_sel_hi:[1,0,1]
	s_nop 0
	v_cvt_pk_bf16_f32 v209, v208, v209
	v_cvt_pk_bf16_f32 v208, v190, v191
	s_nop 1
	v_permlane16_swap_b32_e32 v206, v208
	v_permlane16_swap_b32_e32 v207, v209
	global_store_dwordx4 v229, v[206:209], s[52:53]
	s_waitcnt vmcnt(17)
	v_lshlrev_b32_e32 v190, 16, v210
	v_and_b32_e32 v191, 0xffff0000, v210
	v_lshlrev_b32_e32 v210, 16, v211
	v_and_b32_e32 v211, 0xffff0000, v211
	v_pk_fma_f32 v[210:211], v[210:211], s[16:17], v[14:15] op_sel_hi:[1,0,1]
	v_pk_fma_f32 v[190:191], v[190:191], s[16:17], v[12:13] op_sel_hi:[1,0,1]
	s_nop 0
	v_cvt_pk_bf16_f32 v211, v210, v211
	v_cvt_pk_bf16_f32 v210, v190, v191
	v_lshlrev_b32_e32 v190, 16, v212
	v_and_b32_e32 v191, 0xffff0000, v212
	v_lshlrev_b32_e32 v212, 16, v213
	v_and_b32_e32 v213, 0xffff0000, v213
	v_pk_fma_f32 v[212:213], v[212:213], s[16:17], v[10:11] op_sel_hi:[1,0,1]
	v_pk_fma_f32 v[190:191], v[190:191], s[16:17], v[8:9] op_sel_hi:[1,0,1]
	s_nop 0
	v_cvt_pk_bf16_f32 v213, v212, v213
	v_cvt_pk_bf16_f32 v212, v190, v191
	s_nop 1
	v_permlane16_swap_b32_e32 v210, v212
	v_permlane16_swap_b32_e32 v211, v213
	global_store_dwordx4 v229, v[210:213], s[52:53] offset:256
	s_waitcnt vmcnt(16)
	v_lshlrev_b32_e32 v190, 16, v214
	v_and_b32_e32 v191, 0xffff0000, v214
	v_lshlrev_b32_e32 v214, 16, v215
	v_and_b32_e32 v215, 0xffff0000, v215
	v_pk_fma_f32 v[214:215], v[214:215], s[16:17], v[38:39] op_sel_hi:[1,0,1]
	v_pk_fma_f32 v[190:191], v[190:191], s[16:17], v[36:37] op_sel_hi:[1,0,1]
	s_nop 0
	v_cvt_pk_bf16_f32 v215, v214, v215
	v_cvt_pk_bf16_f32 v214, v190, v191
	v_lshlrev_b32_e32 v190, 16, v216
	v_and_b32_e32 v191, 0xffff0000, v216
	v_lshlrev_b32_e32 v216, 16, v217
	v_and_b32_e32 v217, 0xffff0000, v217
	v_pk_fma_f32 v[216:217], v[216:217], s[16:17], v[34:35] op_sel_hi:[1,0,1]
	v_pk_fma_f32 v[190:191], v[190:191], s[16:17], v[32:33] op_sel_hi:[1,0,1]
	s_nop 0
	v_cvt_pk_bf16_f32 v217, v216, v217
	v_cvt_pk_bf16_f32 v216, v190, v191
	s_nop 1
	v_permlane16_swap_b32_e32 v214, v216
	v_permlane16_swap_b32_e32 v215, v217
	global_store_dwordx4 v230, v[214:217], s[52:53]
	s_waitcnt vmcnt(15)
	v_lshlrev_b32_e32 v190, 16, v218
	v_and_b32_e32 v191, 0xffff0000, v218
	v_lshlrev_b32_e32 v218, 16, v219
	v_and_b32_e32 v219, 0xffff0000, v219
	v_pk_fma_f32 v[218:219], v[218:219], s[16:17], v[6:7] op_sel_hi:[1,0,1]
	v_pk_fma_f32 v[190:191], v[190:191], s[16:17], v[4:5] op_sel_hi:[1,0,1]
	s_nop 0
	v_cvt_pk_bf16_f32 v219, v218, v219
	v_cvt_pk_bf16_f32 v218, v190, v191
	v_lshlrev_b32_e32 v190, 16, v220
	v_and_b32_e32 v191, 0xffff0000, v220
	v_lshlrev_b32_e32 v220, 16, v221
	v_and_b32_e32 v221, 0xffff0000, v221
	v_pk_fma_f32 v[220:221], v[220:221], s[16:17], v[2:3] op_sel_hi:[1,0,1]
	v_pk_fma_f32 v[190:191], v[190:191], s[16:17], v[0:1] op_sel_hi:[1,0,1]
	s_nop 0
	v_cvt_pk_bf16_f32 v221, v220, v221
	v_cvt_pk_bf16_f32 v220, v190, v191
	s_nop 1
	v_permlane16_swap_b32_e32 v218, v220
	v_permlane16_swap_b32_e32 v219, v221
	global_store_dwordx4 v230, v[218:221], s[52:53] offset:256
	s_cbranch_execz .LBB0_909

; __device__ __forceinline__ unsigned pk2(float lo, float hi) { const bf16x2_t v = __builtin_convertvector((f32x2_t){lo, hi}, bf16x2_t); return __builtin_bit_cast(unsigned, v); }
; __device__ __forceinline__ float bf_lo(unsigned w) { return __uint_as_float(w << 16); }
; __device__ __forceinline__ float bf_hi(unsigned w) { return __uint_as_float(w & 0xffff0000u); }
;     __device__ __forceinline__ void row(int ai, int m, const f32x4 (&v)[2][2], const Unit& u, int wr, int wc, int fr, int fq) const {
;         const int row0 = u.pm * BM + wr * 64 + fr, col0 = u.pn * BM + wc * 32 + 4 * fq;
;         const size_t off = (size_t)(row0 + ai * HALF + m * 16) * DM + col0;
; #pragma unroll
;         for (int bj = 0; bj < 2; ++bj)
; #pragma unroll
;             for (int n = 0; n < 2; ++n) { const u32x2 rb = *(const u32x2*)(res + off + bj * HALF + n * 16);
;                 const f32x4 r = (f32x4){bf_lo(rb.x), bf_hi(rb.x), bf_lo(rb.y), bf_hi(rb.y)}; const f32x4 o = v[bj][n] + ALPHA * r;
;                 u32x2 w; w.x = pk2(o[0], o[1]); w.y = pk2(o[2], o[3]); *(u32x2*)(C + off + bj * HALF + n * 16) = w; }
;     }
.LBB0_1256:
	v_lshl_add_u32 v142, s90, 8, v144
	v_lshl_add_u32 v140, s89, 8, v146
	v_lshl_add_u32 v140, v142, 12, v140
	v_lshlrev_b32_e32 v140, 1, v140
	v_add_u32_e32 v141, 0x20000, v140
	v_add_u32_e32 v142, 0x40000, v140
	v_add_u32_e32 v143, 0x60000, v140
	v_add_u32_e32 v150, 0x100000, v140
	v_add_u32_e32 v151, 0x120000, v140
	v_add_u32_e32 v152, 0x140000, v140
	v_add_u32_e32 v153, 0x160000, v140
	v_mbcnt_lo_u32_b32 v222, -1, 0
	v_mbcnt_hi_u32_b32 v222, -1, v222
	v_bfe_u32 v222, v222, 4, 1
	v_mul_u32_u24_e32 v222, 24, v222
	v_add_u32_e32 v223, v140, v222
	v_add_u32_e32 v224, v141, v222
	v_add_u32_e32 v225, v142, v222
	v_add_u32_e32 v226, v143, v222
	v_add_u32_e32 v227, v150, v222
	v_add_u32_e32 v228, v151, v222
	v_add_u32_e32 v229, v152, v222
	v_add_u32_e32 v230, v153, v222
	global_load_dwordx2 v[154:155], v140, s[50:51]
	global_load_dwordx2 v[156:157], v140, s[50:51] offset:32
	global_load_dwordx2 v[158:159], v140, s[50:51] offset:256
	global_load_dwordx2 v[160:161], v140, s[50:51] offset:288
	global_load_dwordx2 v[162:163], v141, s[50:51]
	global_load_dwordx2 v[164:165], v141, s[50:51] offset:32
	global_load_dwordx2 v[166:167], v141, s[50:51] offset:256
	global_load_dwordx2 v[168:169], v141, s[50:51] offset:288
	global_load_dwordx2 v[170:171], v142, s[50:51]
	global_load_dwordx2 v[172:173], v142, s[50:51] offset:32
	global_load_dwordx2 v[174:175], v142, s[50:51] offset:256
	global_load_dwordx2 v[176:177], v142, s[50:51] offset:288
	global_load_dwordx2 v[178:179], v143, s[50:51]
	global_load_dwordx2 v[180:181], v143, s[50:51] offset:32
	global_load_dwordx2 v[182:183], v143, s[50:51] offset:256
	global_load_dwordx2 v[184:185], v143, s[50:51] offset:288
	global_load_dwordx2 v[186:187], v150, s[50:51]
	global_load_dwordx2 v[188:189], v150, s[50:51] offset:32
	global_load_dwordx2 v[194:195], v150, s[50:51] offset:256
	global_load_dwordx2 v[196:197], v150, s[50:51] offset:288
	global_load_dwordx2 v[198:199], v151, s[50:51]
	global_load_dwordx2 v[200:201], v151, s[50:51] offset:32
	global_load_dwordx2 v[202:203], v151, s[50:51] offset:256
	global_load_dwordx2 v[204:205], v151, s[50:51] offset:288
	global_load_dwordx2 v[206:207], v152, s[50:51]
	global_load_dwordx2 v[208:209], v152, s[50:51] offset:32
	global_load_dwordx2 v[210:211], v152, s[50:51] offset:256
	global_load_dwordx2 v[212:213], v152, s[50:51] offset:288
	global_load_dwordx2 v[214:215], v153, s[50:51]
	global_load_dwordx2 v[216:217], v153, s[50:51] offset:32
	global_load_dwordx2 v[218:219], v153, s[50:51] offset:256
	global_load_dwordx2 v[220:221], v153, s[50:51] offset:288
	s_waitcnt vmcnt(30)
	v_lshlrev_b32_e32 v190, 16, v154
	v_and_b32_e32 v191, 0xffff0000, v154
	v_lshlrev_b32_e32 v154, 16, v155
	v_and_b32_e32 v155, 0xffff0000, v155
	v_pk_fma_f32 v[154:155], v[154:155], s[18:19], v[126:127] op_sel_hi:[1,0,1]
	v_pk_fma_f32 v[190:191], v[190:191], s[18:19], v[124:125] op_sel_hi:[1,0,1]
	s_nop 0
	v_cvt_pk_bf16_f32 v155, v154, v155
	v_cvt_pk_bf16_f32 v154, v190, v191
	v_lshlrev_b32_e32 v190, 16, v156
	v_and_b32_e32 v191, 0xffff0000, v156
	v_lshlrev_b32_e32 v156, 16, v157
	v_and_b32_e32 v157, 0xffff0000, v157
	v_pk_fma_f32 v[156:157], v[156:157], s[18:19], v[122:123] op_sel_hi:[1,0,1]
	v_pk_fma_f32 v[190:191], v[190:191], s[18:19], v[120:121] op_sel_hi:[1,0,1]
	s_nop 0
	v_cvt_pk_bf16_f32 v157, v156, v157
	v_cvt_pk_bf16_f32 v156, v190, v191
	s_nop 1
	v_permlane16_swap_b32_e32 v154, v156
	v_permlane16_swap_b32_e32 v155, v157
	global_store_dwordx4 v223, v[154:157], s[52:53]
	s_waitcnt vmcnt(29)
	v_lshlrev_b32_e32 v190, 16, v158
	v_and_b32_e32 v191, 0xffff0000, v158
	v_lshlrev_b32_e32 v158, 16, v159
	v_and_b32_e32 v159, 0xffff0000, v159
	v_pk_fma_f32 v[158:159], v[158:159], s[18:19], v[94:95] op_sel_hi:[1,0,1]
	v_pk_fma_f32 v[190:191], v[190:191], s[18:19], v[92:93] op_sel_hi:[1,0,1]
	s_nop 0
	v_cvt_pk_bf16_f32 v159, v158, v159
	v_cvt_pk_bf16_f32 v158, v190, v191
	v_lshlrev_b32_e32 v190, 16, v160
	v_and_b32_e32 v191, 0xffff0000, v160
	v_lshlrev_b32_e32 v160, 16, v161
	v_and_b32_e32 v161, 0xffff0000, v161
	v_pk_fma_f32 v[160:161], v[160:161], s[18:19], v[90:91] op_sel_hi:[1,0,1]
	v_pk_fma_f32 v[190:191], v[190:191], s[18:19], v[88:89] op_sel_hi:[1,0,1]
	s_nop 0
	v_cvt_pk_bf16_f32 v161, v160, v161
	v_cvt_pk_bf16_f32 v160, v190, v191
	s_nop 1
	v_permlane16_swap_b32_e32 v158, v160
	v_permlane16_swap_b32_e32 v159, v161
	global_store_dwordx4 v223, v[158:161], s[52:53] offset:256
	s_waitcnt vmcnt(28)
	v_lshlrev_b32_e32 v190, 16, v162
	v_and_b32_e32 v191, 0xffff0000, v162
	v_lshlrev_b32_e32 v162, 16, v163
	v_and_b32_e32 v163, 0xffff0000, v163
	v_pk_fma_f32 v[162:163], v[162:163], s[18:19], v[118:119] op_sel_hi:[1,0,1]
	v_pk_fma_f32 v[190:191], v[190:191], s[18:19], v[116:117] op_sel_hi:[1,0,1]
	s_nop 0
	v_cvt_pk_bf16_f32 v163, v162, v163
	v_cvt_pk_bf16_f32 v162, v190, v191
	v_lshlrev_b32_e32 v190, 16, v164
	v_and_b32_e32 v191, 0xffff0000, v164
	v_lshlrev_b32_e32 v164, 16, v165
	v_and_b32_e32 v165, 0xffff0000, v165
	v_pk_fma_f32 v[164:165], v[164:165], s[18:19], v[114:115] op_sel_hi:[1,0,1]
	v_pk_fma_f32 v[190:191], v[190:191], s[18:19], v[112:113] op_sel_hi:[1,0,1]
	s_nop 0
	v_cvt_pk_bf16_f32 v165, v164, v165
	v_cvt_pk_bf16_f32 v164, v190, v191
	s_nop 1
	v_permlane16_swap_b32_e32 v162, v164
	v_permlane16_swap_b32_e32 v163, v165
	global_store_dwordx4 v224, v[162:165], s[52:53]
	s_waitcnt vmcnt(27)
; __device__ __forceinline__ unsigned pk2(float lo, float hi) { const bf16x2_t v = __builtin_convertvector((f32x2_t){lo, hi}, bf16x2_t); return __builtin_bit_cast(unsigned, v); }
; __device__ __forceinline__ float bf_lo(unsigned w) { return __uint_as_float(w << 16); }
; __device__ __forceinline__ float bf_hi(unsigned w) { return __uint_as_float(w & 0xffff0000u); }
;     __device__ __forceinline__ void row(int ai, int m, const f32x4 (&v)[2][2], const Unit& u, int wr, int wc, int fr, int fq) const {
;         const int row0 = u.pm * BM + wr * 64 + fr, col0 = u.pn * BM + wc * 32 + 4 * fq;
;         const size_t off = (size_t)(row0 + ai * HALF + m * 16) * DM + col0;
; #pragma unroll
;         for (int bj = 0; bj < 2; ++bj)
; #pragma unroll
;             for (int n = 0; n < 2; ++n) { const u32x2 rb = *(const u32x2*)(res + off + bj * HALF + n * 16);
;                 const f32x4 r = (f32x4){bf_lo(rb.x), bf_hi(rb.x), bf_lo(rb.y), bf_hi(rb.y)}; const f32x4 o = v[bj][n] + ALPHA * r;
;                 u32x2 w; w.x = pk2(o[0], o[1]); w.y = pk2(o[2], o[3]); *(u32x2*)(C + off + bj * HALF + n * 16) = w; }
;     }
	v_lshlrev_b32_e32 v190, 16, v166
	v_and_b32_e32 v191, 0xffff0000, v166
	v_lshlrev_b32_e32 v166, 16, v167
	v_and_b32_e32 v167, 0xffff0000, v167
	v_pk_fma_f32 v[166:167], v[166:167], s[18:19], v[86:87] op_sel_hi:[1,0,1]
	v_pk_fma_f32 v[190:191], v[190:191], s[18:19], v[84:85] op_sel_hi:[1,0,1]
	s_nop 0
	v_cvt_pk_bf16_f32 v167, v166, v167
	v_cvt_pk_bf16_f32 v166, v190, v191
	v_lshlrev_b32_e32 v190, 16, v168
	v_and_b32_e32 v191, 0xffff0000, v168
	v_lshlrev_b32_e32 v168, 16, v169
	v_and_b32_e32 v169, 0xffff0000, v169
	v_pk_fma_f32 v[168:169], v[168:169], s[18:19], v[82:83] op_sel_hi:[1,0,1]
	v_pk_fma_f32 v[190:191], v[190:191], s[18:19], v[80:81] op_sel_hi:[1,0,1]
	s_nop 0
	v_cvt_pk_bf16_f32 v169, v168, v169
	v_cvt_pk_bf16_f32 v168, v190, v191
	s_nop 1
	v_permlane16_swap_b32_e32 v166, v168
	v_permlane16_swap_b32_e32 v167, v169
	global_store_dwordx4 v224, v[166:169], s[52:53] offset:256
	s_waitcnt vmcnt(26)
	v_lshlrev_b32_e32 v190, 16, v170
	v_and_b32_e32 v191, 0xffff0000, v170
	v_lshlrev_b32_e32 v170, 16, v171
	v_and_b32_e32 v171, 0xffff0000, v171
	v_pk_fma_f32 v[170:171], v[170:171], s[18:19], v[110:111] op_sel_hi:[1,0,1]
	v_pk_fma_f32 v[190:191], v[190:191], s[18:19], v[108:109] op_sel_hi:[1,0,1]
	s_nop 0
	v_cvt_pk_bf16_f32 v171, v170, v171
	v_cvt_pk_bf16_f32 v170, v190, v191
	v_lshlrev_b32_e32 v190, 16, v172
	v_and_b32_e32 v191, 0xffff0000, v172
	v_lshlrev_b32_e32 v172, 16, v173
	v_and_b32_e32 v173, 0xffff0000, v173
	v_pk_fma_f32 v[172:173], v[172:173], s[18:19], v[106:107] op_sel_hi:[1,0,1]
	v_pk_fma_f32 v[190:191], v[190:191], s[18:19], v[104:105] op_sel_hi:[1,0,1]
	s_nop 0
	v_cvt_pk_bf16_f32 v173, v172, v173
	v_cvt_pk_bf16_f32 v172, v190, v191
	s_nop 1
	v_permlane16_swap_b32_e32 v170, v172
	v_permlane16_swap_b32_e32 v171, v173
	global_store_dwordx4 v225, v[170:173], s[52:53]
	s_waitcnt vmcnt(25)
	v_lshlrev_b32_e32 v190, 16, v174
	v_and_b32_e32 v191, 0xffff0000, v174
	v_lshlrev_b32_e32 v174, 16, v175
	v_and_b32_e32 v175, 0xffff0000, v175
	v_pk_fma_f32 v[174:175], v[174:175], s[18:19], v[78:79] op_sel_hi:[1,0,1]
	v_pk_fma_f32 v[190:191], v[190:191], s[18:19], v[76:77] op_sel_hi:[1,0,1]
	s_nop 0
	v_cvt_pk_bf16_f32 v175, v174, v175
	v_cvt_pk_bf16_f32 v174, v190, v191
	v_lshlrev_b32_e32 v190, 16, v176
	v_and_b32_e32 v191, 0xffff0000, v176
	v_lshlrev_b32_e32 v176, 16, v177
	v_and_b32_e32 v177, 0xffff0000, v177
	v_pk_fma_f32 v[176:177], v[176:177], s[18:19], v[74:75] op_sel_hi:[1,0,1]
	v_pk_fma_f32 v[190:191], v[190:191], s[18:19], v[72:73] op_sel_hi:[1,0,1]
	s_nop 0
	v_cvt_pk_bf16_f32 v177, v176, v177
	v_cvt_pk_bf16_f32 v176, v190, v191
	s_nop 1
	v_permlane16_swap_b32_e32 v174, v176
	v_permlane16_swap_b32_e32 v175, v177
	global_store_dwordx4 v225, v[174:177], s[52:53] offset:256
	s_waitcnt vmcnt(24)
	v_lshlrev_b32_e32 v190, 16, v178
	v_and_b32_e32 v191, 0xffff0000, v178
	v_lshlrev_b32_e32 v178, 16, v179
	v_and_b32_e32 v179, 0xffff0000, v179
	v_pk_fma_f32 v[178:179], v[178:179], s[18:19], v[102:103] op_sel_hi:[1,0,1]
	v_pk_fma_f32 v[190:191], v[190:191], s[18:19], v[100:101] op_sel_hi:[1,0,1]
	s_nop 0
	v_cvt_pk_bf16_f32 v179, v178, v179
	v_cvt_pk_bf16_f32 v178, v190, v191
	v_lshlrev_b32_e32 v190, 16, v180
	v_and_b32_e32 v191, 0xffff0000, v180
	v_lshlrev_b32_e32 v180, 16, v181
	v_and_b32_e32 v181, 0xffff0000, v181
	v_pk_fma_f32 v[180:181], v[180:181], s[18:19], v[98:99] op_sel_hi:[1,0,1]
	v_pk_fma_f32 v[190:191], v[190:191], s[18:19], v[96:97] op_sel_hi:[1,0,1]
	s_nop 0
	v_cvt_pk_bf16_f32 v181, v180, v181
	v_cvt_pk_bf16_f32 v180, v190, v191
	s_nop 1
	v_permlane16_swap_b32_e32 v178, v180
	v_permlane16_swap_b32_e32 v179, v181
	global_store_dwordx4 v226, v[178:181], s[52:53]
	s_waitcnt vmcnt(23)
	v_lshlrev_b32_e32 v190, 16, v182
	v_and_b32_e32 v191, 0xffff0000, v182
	v_lshlrev_b32_e32 v182, 16, v183
	v_and_b32_e32 v183, 0xffff0000, v183
	v_pk_fma_f32 v[182:183], v[182:183], s[18:19], v[70:71] op_sel_hi:[1,0,1]
	v_pk_fma_f32 v[190:191], v[190:191], s[18:19], v[68:69] op_sel_hi:[1,0,1]
	s_nop 0
	v_cvt_pk_bf16_f32 v183, v182, v183
	v_cvt_pk_bf16_f32 v182, v190, v191
	v_lshlrev_b32_e32 v190, 16, v184
	v_and_b32_e32 v191, 0xffff0000, v184
	v_lshlrev_b32_e32 v184, 16, v185
	v_and_b32_e32 v185, 0xffff0000, v185
	v_pk_fma_f32 v[184:185], v[184:185], s[18:19], v[66:67] op_sel_hi:[1,0,1]
	v_pk_fma_f32 v[190:191], v[190:191], s[18:19], v[64:65] op_sel_hi:[1,0,1]
	s_nop 0
	v_cvt_pk_bf16_f32 v185, v184, v185
	v_cvt_pk_bf16_f32 v184, v190, v191
	s_nop 1
	v_permlane16_swap_b32_e32 v182, v184
	v_permlane16_swap_b32_e32 v183, v185
	global_store_dwordx4 v226, v[182:185], s[52:53] offset:256
	s_waitcnt vmcnt(22)
	v_lshlrev_b32_e32 v190, 16, v186
	v_and_b32_e32 v191, 0xffff0000, v186
	v_lshlrev_b32_e32 v186, 16, v187
	v_and_b32_e32 v187, 0xffff0000, v187
	v_pk_fma_f32 v[186:187], v[186:187], s[18:19], v[62:63] op_sel_hi:[1,0,1]
	v_pk_fma_f32 v[190:191], v[190:191], s[18:19], v[60:61] op_sel_hi:[1,0,1]
	s_nop 0
	v_cvt_pk_bf16_f32 v187, v186, v187
	v_cvt_pk_bf16_f32 v186, v190, v191
	v_lshlrev_b32_e32 v190, 16, v188
	v_and_b32_e32 v191, 0xffff0000, v188
	v_lshlrev_b32_e32 v188, 16, v189
	v_and_b32_e32 v189, 0xffff0000, v189
	v_pk_fma_f32 v[188:189], v[188:189], s[18:19], v[58:59] op_sel_hi:[1,0,1]
	v_pk_fma_f32 v[190:191], v[190:191], s[18:19], v[56:57] op_sel_hi:[1,0,1]
	s_nop 0
	v_cvt_pk_bf16_f32 v189, v188, v189
	v_cvt_pk_bf16_f32 v188, v190, v191
	s_nop 1
	v_permlane16_swap_b32_e32 v186, v188
	v_permlane16_swap_b32_e32 v187, v189
	global_store_dwordx4 v227, v[186:189], s[52:53]
	s_waitcnt vmcnt(21)
; __device__ __forceinline__ unsigned pk2(float lo, float hi) { const bf16x2_t v = __builtin_convertvector((f32x2_t){lo, hi}, bf16x2_t); return __builtin_bit_cast(unsigned, v); }
; __device__ __forceinline__ float bf_lo(unsigned w) { return __uint_as_float(w << 16); }
; __device__ __forceinline__ float bf_hi(unsigned w) { return __uint_as_float(w & 0xffff0000u); }
;     __device__ __forceinline__ void row(int ai, int m, const f32x4 (&v)[2][2], const Unit& u, int wr, int wc, int fr, int fq) const {
;         const int row0 = u.pm * BM + wr * 64 + fr, col0 = u.pn * BM + wc * 32 + 4 * fq;
;         const size_t off = (size_t)(row0 + ai * HALF + m * 16) * DM + col0;
; #pragma unroll
;         for (int bj = 0; bj < 2; ++bj)
; #pragma unroll
;             for (int n = 0; n < 2; ++n) { const u32x2 rb = *(const u32x2*)(res + off + bj * HALF + n * 16);
;                 const f32x4 r = (f32x4){bf_lo(rb.x), bf_hi(rb.x), bf_lo(rb.y), bf_hi(rb.y)}; const f32x4 o = v[bj][n] + ALPHA * r;
;                 u32x2 w; w.x = pk2(o[0], o[1]); w.y = pk2(o[2], o[3]); *(u32x2*)(C + off + bj * HALF + n * 16) = w; }
;     }
	v_lshlrev_b32_e32 v190, 16, v194
	v_and_b32_e32 v191, 0xffff0000, v194
	v_lshlrev_b32_e32 v194, 16, v195
	v_and_b32_e32 v195, 0xffff0000, v195
	v_pk_fma_f32 v[194:195], v[194:195], s[18:19], v[30:31] op_sel_hi:[1,0,1]
	v_pk_fma_f32 v[190:191], v[190:191], s[18:19], v[28:29] op_sel_hi:[1,0,1]
	s_nop 0
	v_cvt_pk_bf16_f32 v195, v194, v195
	v_cvt_pk_bf16_f32 v194, v190, v191
	v_lshlrev_b32_e32 v190, 16, v196
	v_and_b32_e32 v191, 0xffff0000, v196
	v_lshlrev_b32_e32 v196, 16, v197
	v_and_b32_e32 v197, 0xffff0000, v197
	v_pk_fma_f32 v[196:197], v[196:197], s[18:19], v[26:27] op_sel_hi:[1,0,1]
	v_pk_fma_f32 v[190:191], v[190:191], s[18:19], v[24:25] op_sel_hi:[1,0,1]
	s_nop 0
	v_cvt_pk_bf16_f32 v197, v196, v197
	v_cvt_pk_bf16_f32 v196, v190, v191
	s_nop 1
	v_permlane16_swap_b32_e32 v194, v196
	v_permlane16_swap_b32_e32 v195, v197
	global_store_dwordx4 v227, v[194:197], s[52:53] offset:256
	s_waitcnt vmcnt(20)
	v_lshlrev_b32_e32 v190, 16, v198
	v_and_b32_e32 v191, 0xffff0000, v198
	v_lshlrev_b32_e32 v198, 16, v199
	v_and_b32_e32 v199, 0xffff0000, v199
	v_pk_fma_f32 v[198:199], v[198:199], s[18:19], v[54:55] op_sel_hi:[1,0,1]
	v_pk_fma_f32 v[190:191], v[190:191], s[18:19], v[52:53] op_sel_hi:[1,0,1]
	s_nop 0
	v_cvt_pk_bf16_f32 v199, v198, v199
	v_cvt_pk_bf16_f32 v198, v190, v191
	v_lshlrev_b32_e32 v190, 16, v200
	v_and_b32_e32 v191, 0xffff0000, v200
	v_lshlrev_b32_e32 v200, 16, v201
	v_and_b32_e32 v201, 0xffff0000, v201
	v_pk_fma_f32 v[200:201], v[200:201], s[18:19], v[50:51] op_sel_hi:[1,0,1]
	v_pk_fma_f32 v[190:191], v[190:191], s[18:19], v[48:49] op_sel_hi:[1,0,1]
	s_nop 0
	v_cvt_pk_bf16_f32 v201, v200, v201
	v_cvt_pk_bf16_f32 v200, v190, v191
	s_nop 1
	v_permlane16_swap_b32_e32 v198, v200
	v_permlane16_swap_b32_e32 v199, v201
	global_store_dwordx4 v228, v[198:201], s[52:53]
	s_waitcnt vmcnt(19)
	v_lshlrev_b32_e32 v190, 16, v202
	v_and_b32_e32 v191, 0xffff0000, v202
	v_lshlrev_b32_e32 v202, 16, v203
	v_and_b32_e32 v203, 0xffff0000, v203
	v_pk_fma_f32 v[202:203], v[202:203], s[18:19], v[22:23] op_sel_hi:[1,0,1]
	v_pk_fma_f32 v[190:191], v[190:191], s[18:19], v[20:21] op_sel_hi:[1,0,1]
	s_nop 0
	v_cvt_pk_bf16_f32 v203, v202, v203
	v_cvt_pk_bf16_f32 v202, v190, v191
	v_lshlrev_b32_e32 v190, 16, v204
	v_and_b32_e32 v191, 0xffff0000, v204
	v_lshlrev_b32_e32 v204, 16, v205
	v_and_b32_e32 v205, 0xffff0000, v205
	v_pk_fma_f32 v[204:205], v[204:205], s[18:19], v[18:19] op_sel_hi:[1,0,1]
	v_pk_fma_f32 v[190:191], v[190:191], s[18:19], v[16:17] op_sel_hi:[1,0,1]
	s_nop 0
	v_cvt_pk_bf16_f32 v205, v204, v205
	v_cvt_pk_bf16_f32 v204, v190, v191
	s_nop 1
	v_permlane16_swap_b32_e32 v202, v204
	v_permlane16_swap_b32_e32 v203, v205
	global_store_dwordx4 v228, v[202:205], s[52:53] offset:256
	s_waitcnt vmcnt(18)
	v_lshlrev_b32_e32 v190, 16, v206
	v_and_b32_e32 v191, 0xffff0000, v206
	v_lshlrev_b32_e32 v206, 16, v207
	v_and_b32_e32 v207, 0xffff0000, v207
	v_pk_fma_f32 v[206:207], v[206:207], s[18:19], v[46:47] op_sel_hi:[1,0,1]
	v_pk_fma_f32 v[190:191], v[190:191], s[18:19], v[44:45] op_sel_hi:[1,0,1]
	s_nop 0
	v_cvt_pk_bf16_f32 v207, v206, v207
	v_cvt_pk_bf16_f32 v206, v190, v191
	v_lshlrev_b32_e32 v190, 16, v208
	v_and_b32_e32 v191, 0xffff0000, v208
	v_lshlrev_b32_e32 v208, 16, v209
	v_and_b32_e32 v209, 0xffff0000, v209
	v_pk_fma_f32 v[208:209], v[208:209], s[18:19], v[42:43] op_sel_hi:[1,0,1]
	v_pk_fma_f32 v[190:191], v[190:191], s[18:19], v[40:41] op_sel_hi:[1,0,1]
	s_nop 0
	v_cvt_pk_bf16_f32 v209, v208, v209
	v_cvt_pk_bf16_f32 v208, v190, v191
	s_nop 1
	v_permlane16_swap_b32_e32 v206, v208
	v_permlane16_swap_b32_e32 v207, v209
	global_store_dwordx4 v229, v[206:209], s[52:53]
	s_waitcnt vmcnt(17)
	v_lshlrev_b32_e32 v190, 16, v210
	v_and_b32_e32 v191, 0xffff0000, v210
	v_lshlrev_b32_e32 v210, 16, v211
	v_and_b32_e32 v211, 0xffff0000, v211
	v_pk_fma_f32 v[210:211], v[210:211], s[18:19], v[14:15] op_sel_hi:[1,0,1]
	v_pk_fma_f32 v[190:191], v[190:191], s[18:19], v[12:13] op_sel_hi:[1,0,1]
	s_nop 0
	v_cvt_pk_bf16_f32 v211, v210, v211
	v_cvt_pk_bf16_f32 v210, v190, v191
	v_lshlrev_b32_e32 v190, 16, v212
	v_and_b32_e32 v191, 0xffff0000, v212
	v_lshlrev_b32_e32 v212, 16, v213
	v_and_b32_e32 v213, 0xffff0000, v213
	v_pk_fma_f32 v[212:213], v[212:213], s[18:19], v[10:11] op_sel_hi:[1,0,1]
	v_pk_fma_f32 v[190:191], v[190:191], s[18:19], v[8:9] op_sel_hi:[1,0,1]
	s_nop 0
	v_cvt_pk_bf16_f32 v213, v212, v213
	v_cvt_pk_bf16_f32 v212, v190, v191
	s_nop 1
	v_permlane16_swap_b32_e32 v210, v212
	v_permlane16_swap_b32_e32 v211, v213
	global_store_dwordx4 v229, v[210:213], s[52:53] offset:256
	s_waitcnt vmcnt(16)
	v_lshlrev_b32_e32 v190, 16, v214
	v_and_b32_e32 v191, 0xffff0000, v214
	v_lshlrev_b32_e32 v214, 16, v215
	v_and_b32_e32 v215, 0xffff0000, v215
	v_pk_fma_f32 v[214:215], v[214:215], s[18:19], v[38:39] op_sel_hi:[1,0,1]
	v_pk_fma_f32 v[190:191], v[190:191], s[18:19], v[36:37] op_sel_hi:[1,0,1]
	s_nop 0
	v_cvt_pk_bf16_f32 v215, v214, v215
	v_cvt_pk_bf16_f32 v214, v190, v191
	v_lshlrev_b32_e32 v190, 16, v216
	v_and_b32_e32 v191, 0xffff0000, v216
	v_lshlrev_b32_e32 v216, 16, v217
	v_and_b32_e32 v217, 0xffff0000, v217
	v_pk_fma_f32 v[216:217], v[216:217], s[18:19], v[34:35] op_sel_hi:[1,0,1]
	v_pk_fma_f32 v[190:191], v[190:191], s[18:19], v[32:33] op_sel_hi:[1,0,1]
	s_nop 0
	v_cvt_pk_bf16_f32 v217, v216, v217
	v_cvt_pk_bf16_f32 v216, v190, v191
	s_nop 1
	v_permlane16_swap_b32_e32 v214, v216
	v_permlane16_swap_b32_e32 v215, v217
	global_store_dwordx4 v230, v[214:217], s[52:53]
	s_waitcnt vmcnt(15)
	v_lshlrev_b32_e32 v190, 16, v218
	v_and_b32_e32 v191, 0xffff0000, v218
	v_lshlrev_b32_e32 v218, 16, v219
	v_and_b32_e32 v219, 0xffff0000, v219
	v_pk_fma_f32 v[218:219], v[218:219], s[18:19], v[6:7] op_sel_hi:[1,0,1]
	v_pk_fma_f32 v[190:191], v[190:191], s[18:19], v[4:5] op_sel_hi:[1,0,1]
	s_nop 0
	v_cvt_pk_bf16_f32 v219, v218, v219
	v_cvt_pk_bf16_f32 v218, v190, v191
	v_lshlrev_b32_e32 v190, 16, v220
	v_and_b32_e32 v191, 0xffff0000, v220
	v_lshlrev_b32_e32 v220, 16, v221
	v_and_b32_e32 v221, 0xffff0000, v221
	v_pk_fma_f32 v[220:221], v[220:221], s[18:19], v[2:3] op_sel_hi:[1,0,1]
	v_pk_fma_f32 v[190:191], v[190:191], s[18:19], v[0:1] op_sel_hi:[1,0,1]
	s_nop 0
	v_cvt_pk_bf16_f32 v221, v220, v221
	v_cvt_pk_bf16_f32 v220, v190, v191
	s_nop 1
	v_permlane16_swap_b32_e32 v218, v220
	v_permlane16_swap_b32_e32 v219, v221
	global_store_dwordx4 v230, v[218:221], s[52:53] offset:256
	s_cbranch_execz .LBB0_1253
